# SwiGLU epilogue hand-written with packed f32 ops and two interleaved chains (same per-element arithmetic)
# speedup vs baseline: 1.0042x; 1.0018x over previous
; #define PG8_LAS __attribute__((address_space(3)))
; __device__ __forceinline__ unsigned cvt_pk_bf16(float lo, float hi) { unsigned r; asm volatile("v_cvt_pk_bf16_f32 %0, %1, %2" : "=v"(r) : "v"(lo), "v"(hi)); return r; }
; __device__ __forceinline__ float silu_f(float g) { return g * __builtin_amdgcn_rcpf(1.0f + __expf(-g)); }
;     __device__ __forceinline__ void operator()(const f32x4 (&acc)[2][2][4][2], const Unit& u, int wr, int wc, int fr, int fq, PG8_LAS unsigned char*) const {
;         const int row0 = u.pm * BM + wr * 64 + fr, col0 = u.pn * HALF + wc * 32 + 8 * fq;
; #pragma unroll
;         for (int ai = 0; ai < 2; ++ai)
; #pragma unroll
;             for (int m = 0; m < 4; ++m) { bf16_t* rowp = H + (size_t)(row0 + ai * HALF + m * 16) * ldh + col0;
;                 const f32x4 g0 = acc[ai][0][m][0], g1 = acc[ai][0][m][1], u0 = acc[ai][1][m][0], u1 = acc[ai][1][m][1];
;                 u32x4 w;
;                 w.x = cvt_pk_bf16(silu_f(g0[0]) * u0[0], silu_f(g0[1]) * u0[1]); w.y = cvt_pk_bf16(silu_f(g0[2]) * u0[2], silu_f(g0[3]) * u0[3]);
;                 w.z = cvt_pk_bf16(silu_f(g1[0]) * u1[0], silu_f(g1[1]) * u1[1]); w.w = cvt_pk_bf16(silu_f(g1[2]) * u1[2], silu_f(g1[3]) * u1[3]);
;                 *(u32x4*)rowp = w; }
.LBB0_154:
	v_lshl_or_b32 v162, s89, 7, v166
	v_lshl_add_u32 v176, s96, 8, v164
	v_ashrrev_i32_e32 v163, 31, v162
	v_mov_b64_e32 v[160:161], s[92:93]
	v_lshlrev_b64 v[162:163], 1, v[162:163]
	s_mov_b64 s[46:47], -1
	s_mov_b32 s100, 0xbfb8aa3b
	s_mov_b32 s101, 0xbfb8aa3b
	v_mov_b32_e32 v184, v176
	v_mad_i64_i32 v[184:185], s[38:39], v184, s21, v[160:161]
	v_lshl_add_u64 v[184:185], v[184:185], 0, v[162:163]
	v_pk_mul_f32 v[180:181], v[128:129], s[100:101]
	v_pk_mul_f32 v[182:183], v[130:131], s[100:101]
	v_exp_f32_e32 v180, v180
	v_exp_f32_e32 v181, v181
	v_exp_f32_e32 v182, v182
	v_exp_f32_e32 v183, v183
	v_pk_add_f32 v[180:181], v[180:181], 1.0 op_sel_hi:[1,0]
	v_pk_add_f32 v[182:183], v[182:183], 1.0 op_sel_hi:[1,0]
	v_rcp_f32_e32 v180, v180
	v_rcp_f32_e32 v181, v181
	v_rcp_f32_e32 v182, v182
	v_rcp_f32_e32 v183, v183
	v_pk_mul_f32 v[180:181], v[128:129], v[180:181]
	v_pk_mul_f32 v[182:183], v[130:131], v[182:183]
	v_pk_mul_f32 v[180:181], v[180:181], v[124:125]
	v_pk_mul_f32 v[182:183], v[182:183], v[126:127]
	v_cvt_pk_bf16_f32 v124, v180, v181
	v_cvt_pk_bf16_f32 v125, v182, v183
	v_pk_mul_f32 v[180:181], v[120:121], s[100:101]
	v_pk_mul_f32 v[182:183], v[122:123], s[100:101]
	v_exp_f32_e32 v180, v180
	v_exp_f32_e32 v181, v181
	v_exp_f32_e32 v182, v182
	v_exp_f32_e32 v183, v183
	v_pk_add_f32 v[180:181], v[180:181], 1.0 op_sel_hi:[1,0]
	v_pk_add_f32 v[182:183], v[182:183], 1.0 op_sel_hi:[1,0]
	v_rcp_f32_e32 v180, v180
	v_rcp_f32_e32 v181, v181
	v_rcp_f32_e32 v182, v182
	v_rcp_f32_e32 v183, v183
	v_pk_mul_f32 v[180:181], v[120:121], v[180:181]
	v_pk_mul_f32 v[182:183], v[122:123], v[182:183]
	v_pk_mul_f32 v[180:181], v[180:181], v[116:117]
	v_pk_mul_f32 v[182:183], v[182:183], v[118:119]
	v_cvt_pk_bf16_f32 v126, v180, v181
	v_cvt_pk_bf16_f32 v127, v182, v183
	global_store_dwordx4 v[184:185], v[124:127], off
	v_or_b32_e32 v186, 16, v176
	v_mad_i64_i32 v[186:187], s[38:39], v186, s21, v[160:161]
	v_lshl_add_u64 v[186:187], v[186:187], 0, v[162:163]
	v_pk_mul_f32 v[180:181], v[112:113], s[100:101]
	v_pk_mul_f32 v[182:183], v[114:115], s[100:101]
	v_exp_f32_e32 v180, v180
	v_exp_f32_e32 v181, v181
	v_exp_f32_e32 v182, v182
	v_exp_f32_e32 v183, v183
	v_pk_add_f32 v[180:181], v[180:181], 1.0 op_sel_hi:[1,0]
	v_pk_add_f32 v[182:183], v[182:183], 1.0 op_sel_hi:[1,0]
	v_rcp_f32_e32 v180, v180
	v_rcp_f32_e32 v181, v181
	v_rcp_f32_e32 v182, v182
	v_rcp_f32_e32 v183, v183
	v_pk_mul_f32 v[180:181], v[112:113], v[180:181]
	v_pk_mul_f32 v[182:183], v[114:115], v[182:183]
	v_pk_mul_f32 v[180:181], v[180:181], v[108:109]
	v_pk_mul_f32 v[182:183], v[182:183], v[110:111]
	v_cvt_pk_bf16_f32 v108, v180, v181
	v_cvt_pk_bf16_f32 v109, v182, v183
	v_pk_mul_f32 v[180:181], v[104:105], s[100:101]
	v_pk_mul_f32 v[182:183], v[106:107], s[100:101]
	v_exp_f32_e32 v180, v180
	v_exp_f32_e32 v181, v181
	v_exp_f32_e32 v182, v182
	v_exp_f32_e32 v183, v183
	v_pk_add_f32 v[180:181], v[180:181], 1.0 op_sel_hi:[1,0]
	v_pk_add_f32 v[182:183], v[182:183], 1.0 op_sel_hi:[1,0]
	v_rcp_f32_e32 v180, v180
	v_rcp_f32_e32 v181, v181
	v_rcp_f32_e32 v182, v182
	v_rcp_f32_e32 v183, v183
	v_pk_mul_f32 v[180:181], v[104:105], v[180:181]
	v_pk_mul_f32 v[182:183], v[106:107], v[182:183]
	v_pk_mul_f32 v[180:181], v[180:181], v[100:101]
	v_pk_mul_f32 v[182:183], v[182:183], v[102:103]
	v_cvt_pk_bf16_f32 v110, v180, v181
	v_cvt_pk_bf16_f32 v111, v182, v183
	global_store_dwordx4 v[186:187], v[108:111], off
	v_or_b32_e32 v184, 32, v176
	v_mad_i64_i32 v[184:185], s[38:39], v184, s21, v[160:161]
	v_lshl_add_u64 v[184:185], v[184:185], 0, v[162:163]
	v_pk_mul_f32 v[180:181], v[96:97], s[100:101]
	v_pk_mul_f32 v[182:183], v[98:99], s[100:101]
	v_exp_f32_e32 v180, v180
	v_exp_f32_e32 v181, v181
	v_exp_f32_e32 v182, v182
	v_exp_f32_e32 v183, v183
	v_pk_add_f32 v[180:181], v[180:181], 1.0 op_sel_hi:[1,0]
	v_pk_add_f32 v[182:183], v[182:183], 1.0 op_sel_hi:[1,0]
	v_rcp_f32_e32 v180, v180
	v_rcp_f32_e32 v181, v181
	v_rcp_f32_e32 v182, v182
	v_rcp_f32_e32 v183, v183
	v_pk_mul_f32 v[180:181], v[96:97], v[180:181]
	v_pk_mul_f32 v[182:183], v[98:99], v[182:183]
	v_pk_mul_f32 v[180:181], v[180:181], v[92:93]
	v_pk_mul_f32 v[182:183], v[182:183], v[94:95]
	v_cvt_pk_bf16_f32 v92, v180, v181
	v_cvt_pk_bf16_f32 v93, v182, v183
	v_pk_mul_f32 v[180:181], v[88:89], s[100:101]
	v_pk_mul_f32 v[182:183], v[90:91], s[100:101]
	v_exp_f32_e32 v180, v180
	v_exp_f32_e32 v181, v181
	v_exp_f32_e32 v182, v182
	v_exp_f32_e32 v183, v183
	v_pk_add_f32 v[180:181], v[180:181], 1.0 op_sel_hi:[1,0]
	v_pk_add_f32 v[182:183], v[182:183], 1.0 op_sel_hi:[1,0]
	v_rcp_f32_e32 v180, v180
	v_rcp_f32_e32 v181, v181
	v_rcp_f32_e32 v182, v182
	v_rcp_f32_e32 v183, v183
	v_pk_mul_f32 v[180:181], v[88:89], v[180:181]
	v_pk_mul_f32 v[182:183], v[90:91], v[182:183]
	v_pk_mul_f32 v[180:181], v[180:181], v[84:85]
	v_pk_mul_f32 v[182:183], v[182:183], v[86:87]
	v_cvt_pk_bf16_f32 v94, v180, v181
	v_cvt_pk_bf16_f32 v95, v182, v183
	global_store_dwordx4 v[184:185], v[92:95], off
	v_or_b32_e32 v186, 48, v176
	v_mad_i64_i32 v[186:187], s[38:39], v186, s21, v[160:161]
	v_lshl_add_u64 v[186:187], v[186:187], 0, v[162:163]
	v_pk_mul_f32 v[180:181], v[80:81], s[100:101]
	v_pk_mul_f32 v[182:183], v[82:83], s[100:101]
	v_exp_f32_e32 v180, v180
	v_exp_f32_e32 v181, v181
	v_exp_f32_e32 v182, v182
	v_exp_f32_e32 v183, v183
	v_pk_add_f32 v[180:181], v[180:181], 1.0 op_sel_hi:[1,0]
	v_pk_add_f32 v[182:183], v[182:183], 1.0 op_sel_hi:[1,0]
	v_rcp_f32_e32 v180, v180
	v_rcp_f32_e32 v181, v181
	v_rcp_f32_e32 v182, v182
	v_rcp_f32_e32 v183, v183
	v_pk_mul_f32 v[180:181], v[80:81], v[180:181]
	v_pk_mul_f32 v[182:183], v[82:83], v[182:183]
	v_pk_mul_f32 v[180:181], v[180:181], v[76:77]
; #define PG8_LAS __attribute__((address_space(3)))
; __device__ __forceinline__ unsigned cvt_pk_bf16(float lo, float hi) { unsigned r; asm volatile("v_cvt_pk_bf16_f32 %0, %1, %2" : "=v"(r) : "v"(lo), "v"(hi)); return r; }
; __device__ __forceinline__ float silu_f(float g) { return g * __builtin_amdgcn_rcpf(1.0f + __expf(-g)); }
;     __device__ __forceinline__ void operator()(const f32x4 (&acc)[2][2][4][2], const Unit& u, int wr, int wc, int fr, int fq, PG8_LAS unsigned char*) const {
;         const int row0 = u.pm * BM + wr * 64 + fr, col0 = u.pn * HALF + wc * 32 + 8 * fq;
; #pragma unroll
;         for (int ai = 0; ai < 2; ++ai)
; #pragma unroll
;             for (int m = 0; m < 4; ++m) { bf16_t* rowp = H + (size_t)(row0 + ai * HALF + m * 16) * ldh + col0;
;                 const f32x4 g0 = acc[ai][0][m][0], g1 = acc[ai][0][m][1], u0 = acc[ai][1][m][0], u1 = acc[ai][1][m][1];
;                 u32x4 w;
;                 w.x = cvt_pk_bf16(silu_f(g0[0]) * u0[0], silu_f(g0[1]) * u0[1]); w.y = cvt_pk_bf16(silu_f(g0[2]) * u0[2], silu_f(g0[3]) * u0[3]);
;                 w.z = cvt_pk_bf16(silu_f(g1[0]) * u1[0], silu_f(g1[1]) * u1[1]); w.w = cvt_pk_bf16(silu_f(g1[2]) * u1[2], silu_f(g1[3]) * u1[3]);
;                 *(u32x4*)rowp = w; }
	v_pk_mul_f32 v[182:183], v[182:183], v[78:79]
	v_cvt_pk_bf16_f32 v76, v180, v181
	v_cvt_pk_bf16_f32 v77, v182, v183
	v_pk_mul_f32 v[180:181], v[72:73], s[100:101]
	v_pk_mul_f32 v[182:183], v[74:75], s[100:101]
	v_exp_f32_e32 v180, v180
	v_exp_f32_e32 v181, v181
	v_exp_f32_e32 v182, v182
	v_exp_f32_e32 v183, v183
	v_pk_add_f32 v[180:181], v[180:181], 1.0 op_sel_hi:[1,0]
	v_pk_add_f32 v[182:183], v[182:183], 1.0 op_sel_hi:[1,0]
	v_rcp_f32_e32 v180, v180
	v_rcp_f32_e32 v181, v181
	v_rcp_f32_e32 v182, v182
	v_rcp_f32_e32 v183, v183
	v_pk_mul_f32 v[180:181], v[72:73], v[180:181]
	v_pk_mul_f32 v[182:183], v[74:75], v[182:183]
	v_pk_mul_f32 v[180:181], v[180:181], v[68:69]
	v_pk_mul_f32 v[182:183], v[182:183], v[70:71]
	v_cvt_pk_bf16_f32 v78, v180, v181
	v_cvt_pk_bf16_f32 v79, v182, v183
	global_store_dwordx4 v[186:187], v[76:79], off
	v_add_u32_e32 v184, 0x80, v176
	v_mad_i64_i32 v[184:185], s[38:39], v184, s21, v[160:161]
	v_lshl_add_u64 v[184:185], v[184:185], 0, v[162:163]
	v_pk_mul_f32 v[180:181], v[64:65], s[100:101]
	v_pk_mul_f32 v[182:183], v[66:67], s[100:101]
	v_exp_f32_e32 v180, v180
	v_exp_f32_e32 v181, v181
	v_exp_f32_e32 v182, v182
	v_exp_f32_e32 v183, v183
	v_pk_add_f32 v[180:181], v[180:181], 1.0 op_sel_hi:[1,0]
	v_pk_add_f32 v[182:183], v[182:183], 1.0 op_sel_hi:[1,0]
	v_rcp_f32_e32 v180, v180
	v_rcp_f32_e32 v181, v181
	v_rcp_f32_e32 v182, v182
	v_rcp_f32_e32 v183, v183
	v_pk_mul_f32 v[180:181], v[64:65], v[180:181]
	v_pk_mul_f32 v[182:183], v[66:67], v[182:183]
	v_pk_mul_f32 v[180:181], v[180:181], v[60:61]
	v_pk_mul_f32 v[182:183], v[182:183], v[62:63]
	v_cvt_pk_bf16_f32 v60, v180, v181
	v_cvt_pk_bf16_f32 v61, v182, v183
	v_pk_mul_f32 v[180:181], v[56:57], s[100:101]
	v_pk_mul_f32 v[182:183], v[58:59], s[100:101]
	v_exp_f32_e32 v180, v180
	v_exp_f32_e32 v181, v181
	v_exp_f32_e32 v182, v182
	v_exp_f32_e32 v183, v183
	v_pk_add_f32 v[180:181], v[180:181], 1.0 op_sel_hi:[1,0]
	v_pk_add_f32 v[182:183], v[182:183], 1.0 op_sel_hi:[1,0]
	v_rcp_f32_e32 v180, v180
	v_rcp_f32_e32 v181, v181
	v_rcp_f32_e32 v182, v182
	v_rcp_f32_e32 v183, v183
	v_pk_mul_f32 v[180:181], v[56:57], v[180:181]
	v_pk_mul_f32 v[182:183], v[58:59], v[182:183]
	v_pk_mul_f32 v[180:181], v[180:181], v[52:53]
	v_pk_mul_f32 v[182:183], v[182:183], v[54:55]
	v_cvt_pk_bf16_f32 v62, v180, v181
	v_cvt_pk_bf16_f32 v63, v182, v183
	global_store_dwordx4 v[184:185], v[60:63], off
	v_add_u32_e32 v186, 0x90, v176
	v_mad_i64_i32 v[186:187], s[38:39], v186, s21, v[160:161]
	v_lshl_add_u64 v[186:187], v[186:187], 0, v[162:163]
	v_pk_mul_f32 v[180:181], v[48:49], s[100:101]
	v_pk_mul_f32 v[182:183], v[50:51], s[100:101]
	v_exp_f32_e32 v180, v180
	v_exp_f32_e32 v181, v181
	v_exp_f32_e32 v182, v182
	v_exp_f32_e32 v183, v183
	v_pk_add_f32 v[180:181], v[180:181], 1.0 op_sel_hi:[1,0]
	v_pk_add_f32 v[182:183], v[182:183], 1.0 op_sel_hi:[1,0]
	v_rcp_f32_e32 v180, v180
	v_rcp_f32_e32 v181, v181
	v_rcp_f32_e32 v182, v182
	v_rcp_f32_e32 v183, v183
	v_pk_mul_f32 v[180:181], v[48:49], v[180:181]
	v_pk_mul_f32 v[182:183], v[50:51], v[182:183]
	v_pk_mul_f32 v[180:181], v[180:181], v[44:45]
	v_pk_mul_f32 v[182:183], v[182:183], v[46:47]
	v_cvt_pk_bf16_f32 v44, v180, v181
	v_cvt_pk_bf16_f32 v45, v182, v183
	v_pk_mul_f32 v[180:181], v[40:41], s[100:101]
	v_pk_mul_f32 v[182:183], v[42:43], s[100:101]
	v_exp_f32_e32 v180, v180
	v_exp_f32_e32 v181, v181
	v_exp_f32_e32 v182, v182
	v_exp_f32_e32 v183, v183
	v_pk_add_f32 v[180:181], v[180:181], 1.0 op_sel_hi:[1,0]
	v_pk_add_f32 v[182:183], v[182:183], 1.0 op_sel_hi:[1,0]
	v_rcp_f32_e32 v180, v180
	v_rcp_f32_e32 v181, v181
; __device__ __forceinline__ unsigned cvt_pk_bf16(float lo, float hi) { unsigned r; asm volatile("v_cvt_pk_bf16_f32 %0, %1, %2" : "=v"(r) : "v"(lo), "v"(hi)); return r; }
; __device__ __forceinline__ float silu_f(float g) { return g * __builtin_amdgcn_rcpf(1.0f + __expf(-g)); }
; #define PG8_BAR __builtin_amdgcn_s_barrier()
;     __device__ __forceinline__ void operator()(const f32x4 (&acc)[2][2][4][2], const Unit& u, int wr, int wc, int fr, int fq, PG8_LAS unsigned char*) const {
;     ...
;         for (int ai = 0; ai < 2; ++ai)
; #pragma unroll
;             for (int m = 0; m < 4; ++m) { bf16_t* rowp = H + (size_t)(row0 + ai * HALF + m * 16) * ldh + col0;
;                 const f32x4 g0 = acc[ai][0][m][0], g1 = acc[ai][0][m][1], u0 = acc[ai][1][m][0], u1 = acc[ai][1][m][1];
;                 u32x4 w;
;                 w.x = cvt_pk_bf16(silu_f(g0[0]) * u0[0], silu_f(g0[1]) * u0[1]); w.y = cvt_pk_bf16(silu_f(g0[2]) * u0[2], silu_f(g0[3]) * u0[3]);
;                 w.z = cvt_pk_bf16(silu_f(g1[0]) * u1[0], silu_f(g1[1]) * u1[1]); w.w = cvt_pk_bf16(silu_f(g1[2]) * u1[2], silu_f(g1[3]) * u1[3]);
;                 *(u32x4*)rowp = w; }
; template <class Epi, class Sched, bool ALIGN_EPI = false, bool SP2 = false>
; __device__ __forceinline__ void gemm_phase(PG8_LAS unsigned char* lds, const Gemm g, const Sched& S, const Epi& E) {
;     ...
;         if (!has_next) break;
; #pragma unroll
;         for (int a = 0; a < 2; ++a)
; #pragma unroll
;             for (int b = 0; b < 2; ++b)
; #pragma unroll
;                 for (int m = 0; m < 4; ++m)
; #pragma unroll
;                     for (int n = 0; n < 2; ++n) acc[a][b][m][n] = (f32x4){0.f, 0.f, 0.f, 0.f};
;         cur = nxt; cA = nA; cB = nB; ++ui;
;         if constexpr (ALIGN_EPI) { if (wr == 1) PG8_BAR; }
	v_rcp_f32_e32 v182, v182
	v_rcp_f32_e32 v183, v183
	v_pk_mul_f32 v[180:181], v[40:41], v[180:181]
	v_pk_mul_f32 v[182:183], v[42:43], v[182:183]
	v_pk_mul_f32 v[180:181], v[180:181], v[36:37]
	v_pk_mul_f32 v[182:183], v[182:183], v[38:39]
	v_cvt_pk_bf16_f32 v46, v180, v181
	v_cvt_pk_bf16_f32 v47, v182, v183
	global_store_dwordx4 v[186:187], v[44:47], off
	v_add_u32_e32 v184, 0xa0, v176
	v_mad_i64_i32 v[184:185], s[38:39], v184, s21, v[160:161]
	v_lshl_add_u64 v[184:185], v[184:185], 0, v[162:163]
	v_pk_mul_f32 v[180:181], v[32:33], s[100:101]
	v_pk_mul_f32 v[182:183], v[34:35], s[100:101]
	v_exp_f32_e32 v180, v180
	v_exp_f32_e32 v181, v181
	v_exp_f32_e32 v182, v182
	v_exp_f32_e32 v183, v183
	v_pk_add_f32 v[180:181], v[180:181], 1.0 op_sel_hi:[1,0]
	v_pk_add_f32 v[182:183], v[182:183], 1.0 op_sel_hi:[1,0]
	v_rcp_f32_e32 v180, v180
	v_rcp_f32_e32 v181, v181
	v_rcp_f32_e32 v182, v182
	v_rcp_f32_e32 v183, v183
	v_pk_mul_f32 v[180:181], v[32:33], v[180:181]
	v_pk_mul_f32 v[182:183], v[34:35], v[182:183]
	v_pk_mul_f32 v[180:181], v[180:181], v[28:29]
	v_pk_mul_f32 v[182:183], v[182:183], v[30:31]
	v_cvt_pk_bf16_f32 v28, v180, v181
	v_cvt_pk_bf16_f32 v29, v182, v183
	v_pk_mul_f32 v[180:181], v[24:25], s[100:101]
	v_pk_mul_f32 v[182:183], v[26:27], s[100:101]
	v_exp_f32_e32 v180, v180
	v_exp_f32_e32 v181, v181
	v_exp_f32_e32 v182, v182
	v_exp_f32_e32 v183, v183
	v_pk_add_f32 v[180:181], v[180:181], 1.0 op_sel_hi:[1,0]
	v_pk_add_f32 v[182:183], v[182:183], 1.0 op_sel_hi:[1,0]
	v_rcp_f32_e32 v180, v180
	v_rcp_f32_e32 v181, v181
	v_rcp_f32_e32 v182, v182
	v_rcp_f32_e32 v183, v183
	v_pk_mul_f32 v[180:181], v[24:25], v[180:181]
	v_pk_mul_f32 v[182:183], v[26:27], v[182:183]
	v_pk_mul_f32 v[180:181], v[180:181], v[20:21]
	v_pk_mul_f32 v[182:183], v[182:183], v[22:23]
	v_cvt_pk_bf16_f32 v30, v180, v181
	v_cvt_pk_bf16_f32 v31, v182, v183
	global_store_dwordx4 v[184:185], v[28:31], off
	v_add_u32_e32 v186, 0xb0, v176
	v_mad_i64_i32 v[186:187], s[38:39], v186, s21, v[160:161]
	v_lshl_add_u64 v[186:187], v[186:187], 0, v[162:163]
	v_pk_mul_f32 v[180:181], v[16:17], s[100:101]
	v_pk_mul_f32 v[182:183], v[18:19], s[100:101]
	v_exp_f32_e32 v180, v180
	v_exp_f32_e32 v181, v181
	v_exp_f32_e32 v182, v182
	v_exp_f32_e32 v183, v183
	v_pk_add_f32 v[180:181], v[180:181], 1.0 op_sel_hi:[1,0]
	v_pk_add_f32 v[182:183], v[182:183], 1.0 op_sel_hi:[1,0]
	v_rcp_f32_e32 v180, v180
	v_rcp_f32_e32 v181, v181
	v_rcp_f32_e32 v182, v182
	v_rcp_f32_e32 v183, v183
	v_pk_mul_f32 v[180:181], v[16:17], v[180:181]
	v_pk_mul_f32 v[182:183], v[18:19], v[182:183]
	v_pk_mul_f32 v[180:181], v[180:181], v[12:13]
	v_pk_mul_f32 v[182:183], v[182:183], v[14:15]
	v_cvt_pk_bf16_f32 v12, v180, v181
	v_cvt_pk_bf16_f32 v13, v182, v183
	v_pk_mul_f32 v[180:181], v[8:9], s[100:101]
	v_pk_mul_f32 v[182:183], v[10:11], s[100:101]
	v_exp_f32_e32 v180, v180
	v_exp_f32_e32 v181, v181
	v_exp_f32_e32 v182, v182
	v_exp_f32_e32 v183, v183
	v_pk_add_f32 v[180:181], v[180:181], 1.0 op_sel_hi:[1,0]
	v_pk_add_f32 v[182:183], v[182:183], 1.0 op_sel_hi:[1,0]
	v_rcp_f32_e32 v180, v180
	v_rcp_f32_e32 v181, v181
	v_rcp_f32_e32 v182, v182
	v_rcp_f32_e32 v183, v183
	v_pk_mul_f32 v[180:181], v[8:9], v[180:181]
	v_pk_mul_f32 v[182:183], v[10:11], v[182:183]
	v_pk_mul_f32 v[180:181], v[180:181], v[4:5]
	v_pk_mul_f32 v[182:183], v[182:183], v[6:7]
	v_cvt_pk_bf16_f32 v14, v180, v181
	v_cvt_pk_bf16_f32 v15, v182, v183
	global_store_dwordx4 v[186:187], v[12:15], off
	s_andn2_b64 vcc, exec, s[42:43]
	s_cbranch_vccnz .LBB0_147
	s_andn2_b64 vcc, exec, s[2:3]
	s_cbranch_vccnz .LBB0_146
	s_barrier
	s_branch .LBB0_146
